# S5 output pass: d-skip pointer fetched once before the item loop (was a dependent fetch inside every item ahead of its remaining loads)
# baseline (speedup 1.0000x reference)
; #define LAS __attribute__((address_space(3)))
; template <bool OUT> __device__ __forceinline__ void s5_item(const PA& a, LAS unsigned char* lds, int layer, int item, int wave, int lane) {
;     const int b = item >> 10, g = (item >> 6) & 15, c = item & 63, lg = layer * 16 + g;
;     const bf16* PROJ = (const bf16*)(a.ws + WS_PROJ);
;     const float* sa = (const float*)(a.ws + WS_S5A) + (size_t)lg * 256;
;     float* XL = (float*)(a.ws + WS_XLOC) + (size_t)((b * 16 + g) * 64) * 128;
;     const float ar = sa[lane], ai = sa[64 + lane];
;     float xr = 0.f, xi = 0.f;
;     if (OUT) { xr = XL[c * 128 + lane]; xi = XL[c * 128 + 64 + lane]; }
;     const int l15 = lane & 15, quad = lane >> 4;
;     const bf16x8 zero8 = {0, 0, 0, 0, 0, 0, 0, 0};
;     bf16x8 bfr[8];
; #pragma unroll
;     for (int nt = 0; nt < 8; ++nt) bfr[nt] = (quad < 2) ? *(const bf16x8*)((const bf16*)(a.ws + WS_S5B) + (size_t)lg * 2048 + (nt * 16 + l15) * 16 + quad * 8) : zero8;
;     bf16x8 cfr[4];
;     if (OUT) {
; #pragma unroll
;         for (int ks = 0; ks < 4; ++ks) cfr[ks] = *(const bf16x8*)((const bf16*)(a.ws + WS_S5C) + (size_t)lg * 2048 + l15 * 128 + ks * 32 + quad * 8);
;     }
;     const float dsk = a.in[13][layer * 256 + g * 16 + l15];
;     LAS float* BU = (LAS float*)(lds + wave * 12800);
;     LAS bf16* X = (LAS bf16*)(lds + wave * 12800 + 8448);
;     const size_t rowb = (size_t)b * T + (size_t)c * 128;
.LBB0_671:
	s_ashr_i32 s2, s8, 6
	v_readlane_b32 s0, v253, 6
	s_add_i32 s12, s2, s0
	s_cmpk_gt_i32 s12, 0x7ff
	s_barrier
	s_cbranch_scc1 .LBB0_705
	v_readlane_b32 s8, v252, 20
	v_and_b32_e32 v91, 63, v0
	v_and_b32_e32 v90, 15, v0
	v_bfe_u32 v4, v0, 4, 2
	v_and_b32_e32 v0, 48, v0
	v_mov_b32_e32 v1, v221
	v_readlane_b32 s9, v252, 21
	v_readlane_b32 s3, v254, 44
	v_lshlrev_b32_e32 v2, 8, v90
	v_lshl_add_u64 v[96:97], s[8:9], 0, v[0:1]
	v_readlane_b32 s8, v253, 21
	v_mov_b32_e32 v3, v221
	v_readlane_b32 s9, v253, 22
	s_lshl_b32 s13, s3, 4
	v_lshl_or_b32 v93, s3, 8, v90
	v_lshl_add_u64 v[2:3], s[8:9], 0, v[2:3]
	s_mul_i32 s3, s2, 0x3200
	v_lshlrev_b32_e32 v220, 2, v91
	v_lshl_add_u64 v[98:99], v[2:3], 0, v[0:1]
	s_add_i32 s3, s3, 0
	v_lshlrev_b32_e32 v2, 1, v91
	v_lshlrev_b32_e32 v100, 2, v4
	v_mov_b32_e32 v1, s3
	v_lshl_add_u32 v5, v90, 2, s3
	v_add_u32_e32 v95, s3, v220
	v_sub_u32_e32 v8, 0, v2
	s_lshl_b32 s2, s2, 7
	v_readlane_b32 s3, v254, 14
	v_mul_u32_u24_e32 v2, 0x1c00, v90
	v_readlane_b32 s0, v252, 18
	v_or_b32_e32 v102, 1, v100
	s_movk_i32 s8, 0x110
	s_add_i32 s14, s3, s2
	v_mul_hi_u32_u24_e32 v3, 0x1c00, v90
	v_or_b32_e32 v2, v2, v0
	s_mov_b64 s[2:3], 0x4038800
	v_readlane_b32 s1, v252, 19
	v_mul_u32_u24_e32 v6, 0x840, v4
	v_mul_u32_u24_e32 v7, 0x210, v102
	v_mad_u32_u24 v1, v90, s8, v1
	v_lshl_add_u64 v[112:113], v[2:3], 0, s[2:3]
	v_mul_u32_u24_e32 v2, 0x7000, v4
	v_lshl_add_u64 v[88:89], s[0:1], 0, v[220:221]
	v_cmp_gt_u32_e64 s[0:1], 32, v91
	v_lshlrev_b32_e32 v92, 4, v90
	v_lshlrev_b32_e32 v94, 3, v4
	v_cmp_lt_u32_e64 s[38:39], 31, v91
	v_mov_b32_e32 v101, v221
	v_or_b32_e32 v104, 2, v100
	v_or_b32_e32 v106, 3, v100
	v_or_b32_e32 v108, 16, v91
	v_lshlrev_b32_e32 v110, 11, v4
	v_mul_hi_u32_u24_e32 v115, 0x7000, v4
	v_lshl_or_b32 v114, v90, 1, v2
	v_lshlrev_b32_e32 v116, 1, v90
	v_add_u32_e32 v103, v1, v0
	v_add_u32_e32 v105, v5, v6
	v_add_u32_e32 v107, v5, v7
	v_add_u32_e32 v109, v95, v8
	v_readlane_b32 s8, v253, 23
	v_readlane_b32 s9, v253, 24
	s_nop 4
	global_load_dwordx2 v[194:195], v221, s[8:9]
	s_branch .LBB0_674

; #define LAS __attribute__((address_space(3)))
; template <bool OUT> __device__ __forceinline__ void s5_item(const PA& a, LAS unsigned char* lds, int layer, int item, int wave, int lane) {
;     ...
;     for (int nt = 0; nt < 8; ++nt) bfr[nt] = (quad < 2) ? *(const bf16x8*)((const bf16*)(a.ws + WS_S5B) + (size_t)lg * 2048 + (nt * 16 + l15) * 16 + quad * 8) : zero8;
;     bf16x8 cfr[4];
;     if (OUT) {
; #pragma unroll
;         for (int ks = 0; ks < 4; ++ks) cfr[ks] = *(const bf16x8*)((const bf16*)(a.ws + WS_S5C) + (size_t)lg * 2048 + l15 * 128 + ks * 32 + quad * 8);
;     }
;     const float dsk = a.in[13][layer * 256 + g * 16 + l15];
;     LAS float* BU = (LAS float*)(lds + wave * 12800);
;     LAS bf16* X = (LAS bf16*)(lds + wave * 12800 + 8448);
;     const size_t rowb = (size_t)b * T + (size_t)c * 128;
;     bf16x8 afr_n = (quad < 2) ? *(const bf16x8*)(PROJ + (rowb + l15) * DIN + 1024 + g * 16 + quad * 8) : zero8;
.LBB0_690:
	s_or_b64 exec, exec, s[8:9]
	v_readlane_b32 s8, v253, 23
	v_readlane_b32 s9, v253, 24
	v_lshl_add_u64 v[44:45], v[98:99], 0, s[2:3]
	s_lshl_b32 s62, s10, 4
	v_or_b32_e32 v220, s62, v93
	v_lshlrev_b32_e32 v84, 1, v94
	s_nop 0
	global_load_dwordx4 v[32:35], v[44:45], off
	global_load_dwordx4 v[36:39], v[44:45], off offset:64
	global_load_dwordx4 v[40:43], v[44:45], off offset:128
	s_nop 0
	global_load_dwordx4 v[44:47], v[44:45], off offset:192
	s_ashr_i32 s8, s12, 10
	s_ashr_i32 s9, s8, 31
	s_lshl_b64 s[2:3], s[8:9], 13
	s_or_b32 s15, s2, s11
	s_mul_i32 s20, s3, 0x1c00
	s_waitcnt vmcnt(16)
	v_lshl_add_u64 v[48:49], v[220:221], 2, v[194:195]
	flat_load_dword v111, v[48:49]
	v_mov_b64_e32 v[48:49], s[62:63]
	s_and_saveexec_b64 s[10:11], s[0:1]
	s_xor_b64 s[10:11], exec, s[10:11]
	s_cbranch_execz .LBB0_692
	v_or_b32_e32 v50, s15, v90
	v_mov_b64_e32 v[48:49], s[60:61]
	v_mad_u64_u32 v[48:49], s[22:23], v50, s93, v[48:49]
	v_add_u32_e32 v49, s20, v49
	s_lshl_b32 s22, s62, 1
	s_mov_b32 s23, s63
	v_lshl_add_u64 v[48:49], v[48:49], 0, s[22:23]
	v_mov_b32_e32 v85, v221
	v_lshl_add_u64 v[48:49], v[48:49], 0, v[84:85]
	global_load_dwordx4 v[76:79], v[48:49], off offset:2048
	v_mov_b64_e32 v[48:49], s[62:63]
